# P6 epilogue x loads use the default cache policy instead of nt
# baseline (speedup 1.0000x reference)
.Lp6_prompt:
	v_add_u32_e32 v3, s35, v245
	v_lshlrev_b32_e32 v251, 2, v3
	global_load_dwordx4 v[68:71], v251, s[80:81]
	global_load_dwordx4 v[72:75], v251, s[80:81] offset:64
	global_load_dwordx4 v[76:79], v251, s[80:81] offset:512
	global_load_dwordx4 v[80:83], v251, s[80:81] offset:576
	global_load_dwordx4 v[92:95], v251, s[46:47]
	global_load_dwordx4 v[96:99], v251, s[46:47] offset:64
	global_load_dwordx4 v[100:103], v251, s[46:47] offset:512
	global_load_dwordx4 v[84:87], v251, s[46:47] offset:576
	v_add_u32_e32 v1, s38, v244
	v_lshlrev_b32_e32 v251, 2, v1
	v_lshl_add_u32 v1, v1, 11, v3
	v_bfe_u32 v3, v245, 2, 1
	v_mul_u32_u24_e32 v3, 24, v3
	v_lshl_add_u32 v240, v1, 1, v3
	v_lshlrev_b32_e32 v1, 2, v1
	s_cmp_gt_i32 s79, 0
	s_cbranch_scc1 .Lp6_quart
	v_mov_b32_e32 v236, v1
	global_load_dwordx4 v[164:167], v236, s[82:83] offset:0
	global_load_dwordx4 v[168:171], v236, s[82:83] offset:64
	global_load_dwordx4 v[172:175], v236, s[82:83] offset:512
	global_load_dwordx4 v[176:179], v236, s[82:83] offset:576
	v_add_u32_e32 v237, 0x20000, v1
	global_load_dwordx4 v[180:183], v237, s[82:83] offset:0
	global_load_dwordx4 v[184:187], v237, s[82:83] offset:64
	global_load_dwordx4 v[188:191], v237, s[82:83] offset:512
	global_load_dwordx4 v[192:195], v237, s[82:83] offset:576
	v_add_u32_e32 v236, 0x40000, v1
	global_load_dwordx4 v[196:199], v236, s[82:83] offset:0
	global_load_dwordx4 v[200:203], v236, s[82:83] offset:64
	global_load_dwordx4 v[204:207], v236, s[82:83] offset:512
	global_load_dwordx4 v[208:211], v236, s[82:83] offset:576
	v_add_u32_e32 v237, 0x60000, v1
	global_load_dwordx4 v[212:215], v237, s[82:83] offset:0
	s_waitcnt vmcnt(12)
	v_mov_b32_e32 v238, v1
	v_mov_b32_e32 v239, v240
	v_pk_fma_f32 v[160:161], v[160:161], v[68:69], v[164:165]
	v_pk_fma_f32 v[162:163], v[162:163], v[70:71], v[166:167]
	global_store_dwordx4 v238, v[160:163], s[94:95] offset:0
	v_pk_mul_f32 v[2:3], v[160:161], v[160:161]
	v_pk_fma_f32 v[2:3], v[162:163], v[162:163], v[2:3]
	v_pk_mul_f32 v[164:165], v[160:161], v[92:93]
	v_pk_mul_f32 v[166:167], v[162:163], v[94:95]
	v_cvt_pk_bf16_f32 v216, v164, v165
	v_cvt_pk_bf16_f32 v217, v166, v167
	global_load_dwordx4 v[164:167], v237, s[82:83] offset:64
	s_waitcnt vmcnt(13)
	v_pk_fma_f32 v[156:157], v[156:157], v[72:73], v[168:169]
	v_pk_fma_f32 v[158:159], v[158:159], v[74:75], v[170:171]
	global_store_dwordx4 v238, v[156:159], s[94:95] offset:64
	v_pk_fma_f32 v[2:3], v[156:157], v[156:157], v[2:3]
	v_pk_fma_f32 v[2:3], v[158:159], v[158:159], v[2:3]
	v_pk_mul_f32 v[168:169], v[156:157], v[96:97]
	v_pk_mul_f32 v[170:171], v[158:159], v[98:99]
	v_cvt_pk_bf16_f32 v218, v168, v169
	v_cvt_pk_bf16_f32 v219, v170, v171
	s_nop 1
	v_permlane16_swap_b32 v216, v218
	v_permlane16_swap_b32 v217, v219
	global_store_dwordx4 v239, v[216:219], s[10:11] offset:0
	global_load_dwordx4 v[168:171], v237, s[82:83] offset:512
	s_waitcnt vmcnt(15)
	v_pk_fma_f32 v[144:145], v[144:145], v[76:77], v[172:173]
	v_pk_fma_f32 v[146:147], v[146:147], v[78:79], v[174:175]
	global_store_dwordx4 v238, v[144:147], s[94:95] offset:512
	v_pk_fma_f32 v[2:3], v[144:145], v[144:145], v[2:3]
	v_pk_fma_f32 v[2:3], v[146:147], v[146:147], v[2:3]
	v_pk_mul_f32 v[172:173], v[144:145], v[100:101]
	v_pk_mul_f32 v[174:175], v[146:147], v[102:103]
	v_cvt_pk_bf16_f32 v220, v172, v173
	v_cvt_pk_bf16_f32 v221, v174, v175
	global_load_dwordx4 v[172:175], v237, s[82:83] offset:576
	s_waitcnt vmcnt(16)
	v_pk_fma_f32 v[140:141], v[140:141], v[80:81], v[176:177]
	v_pk_fma_f32 v[142:143], v[142:143], v[82:83], v[178:179]
	global_store_dwordx4 v238, v[140:143], s[94:95] offset:576
	v_pk_fma_f32 v[2:3], v[140:141], v[140:141], v[2:3]
	v_pk_fma_f32 v[2:3], v[142:143], v[142:143], v[2:3]
	v_pk_mul_f32 v[176:177], v[140:141], v[84:85]
	v_pk_mul_f32 v[178:179], v[142:143], v[86:87]
	v_cvt_pk_bf16_f32 v222, v176, v177
	v_cvt_pk_bf16_f32 v223, v178, v179
	s_nop 1
	v_permlane16_swap_b32 v220, v222
	v_permlane16_swap_b32 v221, v223
	global_store_dwordx4 v239, v[220:223], s[10:11] offset:256
	v_add_f32_e32 v160, v2, v3
	v_add_u32_e32 v236, 0x100000, v1
	global_load_dwordx4 v[176:179], v236, s[82:83] offset:0
	s_waitcnt vmcnt(18)
	v_add_u32_e32 v238, 0x20000, v1
	v_add_u32_e32 v239, 0x10000, v240
	v_pk_fma_f32 v[152:153], v[152:153], v[68:69], v[180:181]
	v_pk_fma_f32 v[154:155], v[154:155], v[70:71], v[182:183]
	global_store_dwordx4 v238, v[152:155], s[94:95] offset:0
	v_pk_mul_f32 v[2:3], v[152:153], v[152:153]
	v_pk_fma_f32 v[2:3], v[154:155], v[154:155], v[2:3]
	v_pk_mul_f32 v[180:181], v[152:153], v[92:93]
	v_pk_mul_f32 v[182:183], v[154:155], v[94:95]
	v_cvt_pk_bf16_f32 v224, v180, v181
	v_cvt_pk_bf16_f32 v225, v182, v183
	global_load_dwordx4 v[180:183], v236, s[82:83] offset:64
	s_waitcnt vmcnt(19)
	v_pk_fma_f32 v[148:149], v[148:149], v[72:73], v[184:185]
	v_pk_fma_f32 v[150:151], v[150:151], v[74:75], v[186:187]
	global_store_dwordx4 v238, v[148:151], s[94:95] offset:64
	v_pk_fma_f32 v[2:3], v[148:149], v[148:149], v[2:3]
	v_pk_fma_f32 v[2:3], v[150:151], v[150:151], v[2:3]
	v_pk_mul_f32 v[184:185], v[148:149], v[96:97]
	v_pk_mul_f32 v[186:187], v[150:151], v[98:99]
	v_cvt_pk_bf16_f32 v226, v184, v185
	v_cvt_pk_bf16_f32 v227, v186, v187
	s_nop 1
	v_permlane16_swap_b32 v224, v226
	v_permlane16_swap_b32 v225, v227
	global_store_dwordx4 v239, v[224:227], s[10:11] offset:0
	global_load_dwordx4 v[184:187], v236, s[82:83] offset:512
	s_waitcnt vmcnt(21)
	v_pk_fma_f32 v[128:129], v[128:129], v[76:77], v[188:189]
	v_pk_fma_f32 v[130:131], v[130:131], v[78:79], v[190:191]
	global_store_dwordx4 v238, v[128:131], s[94:95] offset:512
	v_pk_fma_f32 v[2:3], v[128:129], v[128:129], v[2:3]
	v_pk_fma_f32 v[2:3], v[130:131], v[130:131], v[2:3]
	v_pk_mul_f32 v[188:189], v[128:129], v[100:101]
	v_pk_mul_f32 v[190:191], v[130:131], v[102:103]
	v_cvt_pk_bf16_f32 v216, v188, v189
	v_cvt_pk_bf16_f32 v217, v190, v191
	global_load_dwordx4 v[188:191], v236, s[82:83] offset:576
	s_waitcnt vmcnt(22)
	v_pk_fma_f32 v[124:125], v[124:125], v[80:81], v[192:193]
	v_pk_fma_f32 v[126:127], v[126:127], v[82:83], v[194:195]
	global_store_dwordx4 v238, v[124:127], s[94:95] offset:576
	v_pk_fma_f32 v[2:3], v[124:125], v[124:125], v[2:3]
	v_pk_fma_f32 v[2:3], v[126:127], v[126:127], v[2:3]
	v_pk_mul_f32 v[192:193], v[124:125], v[84:85]
	v_pk_mul_f32 v[194:195], v[126:127], v[86:87]
	v_cvt_pk_bf16_f32 v218, v192, v193
	v_cvt_pk_bf16_f32 v219, v194, v195
	s_nop 1
	v_permlane16_swap_b32 v216, v218
	v_permlane16_swap_b32 v217, v219
	global_store_dwordx4 v239, v[216:219], s[10:11] offset:256
	v_add_f32_e32 v152, v2, v3
	v_add_u32_e32 v237, 0x120000, v1
	global_load_dwordx4 v[192:195], v237, s[82:83] offset:0
	s_waitcnt vmcnt(24)
	v_add_u32_e32 v238, 0x40000, v1
	v_add_u32_e32 v239, 0x20000, v240
	v_pk_fma_f32 v[136:137], v[136:137], v[68:69], v[196:197]
	v_pk_fma_f32 v[138:139], v[138:139], v[70:71], v[198:199]
	global_store_dwordx4 v238, v[136:139], s[94:95] offset:0
	v_pk_mul_f32 v[2:3], v[136:137], v[136:137]
	v_pk_fma_f32 v[2:3], v[138:139], v[138:139], v[2:3]
	v_pk_mul_f32 v[196:197], v[136:137], v[92:93]
	v_pk_mul_f32 v[198:199], v[138:139], v[94:95]
	v_cvt_pk_bf16_f32 v220, v196, v197
	v_cvt_pk_bf16_f32 v221, v198, v199
	global_load_dwordx4 v[196:199], v237, s[82:83] offset:64
	s_waitcnt vmcnt(25)
	v_pk_fma_f32 v[132:133], v[132:133], v[72:73], v[200:201]
	v_pk_fma_f32 v[134:135], v[134:135], v[74:75], v[202:203]
	global_store_dwordx4 v238, v[132:135], s[94:95] offset:64
	v_pk_fma_f32 v[2:3], v[132:133], v[132:133], v[2:3]
	v_pk_fma_f32 v[2:3], v[134:135], v[134:135], v[2:3]
	v_pk_mul_f32 v[200:201], v[132:133], v[96:97]
	v_pk_mul_f32 v[202:203], v[134:135], v[98:99]
	v_cvt_pk_bf16_f32 v222, v200, v201
	v_cvt_pk_bf16_f32 v223, v202, v203
	s_nop 1
	v_permlane16_swap_b32 v220, v222
	v_permlane16_swap_b32 v221, v223
	global_store_dwordx4 v239, v[220:223], s[10:11] offset:0
	global_load_dwordx4 v[200:203], v237, s[82:83] offset:512
	s_waitcnt vmcnt(27)
	v_pk_fma_f32 v[116:117], v[116:117], v[76:77], v[204:205]
	v_pk_fma_f32 v[118:119], v[118:119], v[78:79], v[206:207]
	global_store_dwordx4 v238, v[116:119], s[94:95] offset:512
	v_pk_fma_f32 v[2:3], v[116:117], v[116:117], v[2:3]
	v_pk_fma_f32 v[2:3], v[118:119], v[118:119], v[2:3]
	v_pk_mul_f32 v[204:205], v[116:117], v[100:101]
	v_pk_mul_f32 v[206:207], v[118:119], v[102:103]
	v_cvt_pk_bf16_f32 v224, v204, v205
	v_cvt_pk_bf16_f32 v225, v206, v207
	global_load_dwordx4 v[204:207], v237, s[82:83] offset:576
	s_waitcnt vmcnt(28)
	v_pk_fma_f32 v[108:109], v[108:109], v[80:81], v[208:209]
	v_pk_fma_f32 v[110:111], v[110:111], v[82:83], v[210:211]
	global_store_dwordx4 v238, v[108:111], s[94:95] offset:576
	v_pk_fma_f32 v[2:3], v[108:109], v[108:109], v[2:3]
	v_pk_fma_f32 v[2:3], v[110:111], v[110:111], v[2:3]
	v_pk_mul_f32 v[208:209], v[108:109], v[84:85]
	v_pk_mul_f32 v[210:211], v[110:111], v[86:87]
	v_cvt_pk_bf16_f32 v226, v208, v209
	v_cvt_pk_bf16_f32 v227, v210, v211
	s_nop 1
	v_permlane16_swap_b32 v224, v226
	v_permlane16_swap_b32 v225, v227
	global_store_dwordx4 v239, v[224:227], s[10:11] offset:256
	v_add_f32_e32 v136, v2, v3
	v_add_u32_e32 v236, 0x140000, v1
	global_load_dwordx4 v[208:211], v236, s[82:83] offset:0
	s_waitcnt vmcnt(30)
	v_add_u32_e32 v238, 0x60000, v1
	v_add_u32_e32 v239, 0x30000, v240
	v_pk_fma_f32 v[120:121], v[120:121], v[68:69], v[212:213]
	v_pk_fma_f32 v[122:123], v[122:123], v[70:71], v[214:215]
	global_store_dwordx4 v238, v[120:123], s[94:95] offset:0
	v_pk_mul_f32 v[2:3], v[120:121], v[120:121]
	v_pk_fma_f32 v[2:3], v[122:123], v[122:123], v[2:3]
	v_pk_mul_f32 v[212:213], v[120:121], v[92:93]
	v_pk_mul_f32 v[214:215], v[122:123], v[94:95]
	v_cvt_pk_bf16_f32 v216, v212, v213
	v_cvt_pk_bf16_f32 v217, v214, v215
	global_load_dwordx4 v[212:215], v236, s[82:83] offset:64
	s_waitcnt vmcnt(30)
	v_pk_fma_f32 v[112:113], v[112:113], v[72:73], v[164:165]
	v_pk_fma_f32 v[114:115], v[114:115], v[74:75], v[166:167]
	global_store_dwordx4 v238, v[112:115], s[94:95] offset:64
	v_pk_fma_f32 v[2:3], v[112:113], v[112:113], v[2:3]
	v_pk_fma_f32 v[2:3], v[114:115], v[114:115], v[2:3]
	v_pk_mul_f32 v[164:165], v[112:113], v[96:97]
	v_pk_mul_f32 v[166:167], v[114:115], v[98:99]
	v_cvt_pk_bf16_f32 v218, v164, v165
	v_cvt_pk_bf16_f32 v219, v166, v167
	s_nop 1
	v_permlane16_swap_b32 v216, v218
	v_permlane16_swap_b32 v217, v219
	global_store_dwordx4 v239, v[216:219], s[10:11] offset:0
	global_load_dwordx4 v[164:167], v236, s[82:83] offset:512
	s_waitcnt vmcnt(30)
	v_pk_fma_f32 v[104:105], v[104:105], v[76:77], v[168:169]
	v_pk_fma_f32 v[106:107], v[106:107], v[78:79], v[170:171]
	global_store_dwordx4 v238, v[104:107], s[94:95] offset:512
	v_pk_fma_f32 v[2:3], v[104:105], v[104:105], v[2:3]
	v_pk_fma_f32 v[2:3], v[106:107], v[106:107], v[2:3]
	v_pk_mul_f32 v[168:169], v[104:105], v[100:101]
	v_pk_mul_f32 v[170:171], v[106:107], v[102:103]
	v_cvt_pk_bf16_f32 v220, v168, v169
	v_cvt_pk_bf16_f32 v221, v170, v171
	global_load_dwordx4 v[168:171], v236, s[82:83] offset:576
	s_waitcnt vmcnt(30)
	v_pk_fma_f32 v[88:89], v[88:89], v[80:81], v[172:173]
	v_pk_fma_f32 v[90:91], v[90:91], v[82:83], v[174:175]
	global_store_dwordx4 v238, v[88:91], s[94:95] offset:576
	v_pk_fma_f32 v[2:3], v[88:89], v[88:89], v[2:3]
	v_pk_fma_f32 v[2:3], v[90:91], v[90:91], v[2:3]
	v_pk_mul_f32 v[172:173], v[88:89], v[84:85]
	v_pk_mul_f32 v[174:175], v[90:91], v[86:87]
	v_cvt_pk_bf16_f32 v222, v172, v173
	v_cvt_pk_bf16_f32 v223, v174, v175
	s_nop 1
	v_permlane16_swap_b32 v220, v222
	v_permlane16_swap_b32 v221, v223
	global_store_dwordx4 v239, v[220:223], s[10:11] offset:256
	v_add_f32_e32 v120, v2, v3
	v_add_u32_e32 v237, 0x160000, v1
	global_load_dwordx4 v[172:175], v237, s[82:83] offset:0
	s_waitcnt vmcnt(30)
	v_add_u32_e32 v238, 0x100000, v1
	v_add_u32_e32 v239, 0x80000, v240
	v_pk_fma_f32 v[64:65], v[64:65], v[68:69], v[176:177]
	v_pk_fma_f32 v[66:67], v[66:67], v[70:71], v[178:179]
	global_store_dwordx4 v238, v[64:67], s[94:95] offset:0
	v_pk_mul_f32 v[2:3], v[64:65], v[64:65]
	v_pk_fma_f32 v[2:3], v[66:67], v[66:67], v[2:3]
	v_pk_mul_f32 v[176:177], v[64:65], v[92:93]
	v_pk_mul_f32 v[178:179], v[66:67], v[94:95]
	v_cvt_pk_bf16_f32 v224, v176, v177
	v_cvt_pk_bf16_f32 v225, v178, v179
	global_load_dwordx4 v[176:179], v237, s[82:83] offset:64
	s_waitcnt vmcnt(30)
	v_pk_fma_f32 v[60:61], v[60:61], v[72:73], v[180:181]
	v_pk_fma_f32 v[62:63], v[62:63], v[74:75], v[182:183]
	global_store_dwordx4 v238, v[60:63], s[94:95] offset:64
	v_pk_fma_f32 v[2:3], v[60:61], v[60:61], v[2:3]
	v_pk_fma_f32 v[2:3], v[62:63], v[62:63], v[2:3]
	v_pk_mul_f32 v[180:181], v[60:61], v[96:97]
	v_pk_mul_f32 v[182:183], v[62:63], v[98:99]
	v_cvt_pk_bf16_f32 v226, v180, v181
	v_cvt_pk_bf16_f32 v227, v182, v183
	s_nop 1
	v_permlane16_swap_b32 v224, v226
	v_permlane16_swap_b32 v225, v227
	global_store_dwordx4 v239, v[224:227], s[10:11] offset:0
	global_load_dwordx4 v[180:183], v237, s[82:83] offset:512
	s_waitcnt vmcnt(30)
	v_pk_fma_f32 v[56:57], v[56:57], v[76:77], v[184:185]
	v_pk_fma_f32 v[58:59], v[58:59], v[78:79], v[186:187]
	global_store_dwordx4 v238, v[56:59], s[94:95] offset:512
	v_pk_fma_f32 v[2:3], v[56:57], v[56:57], v[2:3]
	v_pk_fma_f32 v[2:3], v[58:59], v[58:59], v[2:3]
	v_pk_mul_f32 v[184:185], v[56:57], v[100:101]
	v_pk_mul_f32 v[186:187], v[58:59], v[102:103]
	v_cvt_pk_bf16_f32 v216, v184, v185
	v_cvt_pk_bf16_f32 v217, v186, v187
	global_load_dwordx4 v[184:187], v237, s[82:83] offset:576
	s_waitcnt vmcnt(30)
	v_pk_fma_f32 v[52:53], v[52:53], v[80:81], v[188:189]
	v_pk_fma_f32 v[54:55], v[54:55], v[82:83], v[190:191]
	global_store_dwordx4 v238, v[52:55], s[94:95] offset:576
	v_pk_fma_f32 v[2:3], v[52:53], v[52:53], v[2:3]
	v_pk_fma_f32 v[2:3], v[54:55], v[54:55], v[2:3]
	v_pk_mul_f32 v[188:189], v[52:53], v[84:85]
	v_pk_mul_f32 v[190:191], v[54:55], v[86:87]
	v_cvt_pk_bf16_f32 v218, v188, v189
	v_cvt_pk_bf16_f32 v219, v190, v191
	s_nop 1
	v_permlane16_swap_b32 v216, v218
	v_permlane16_swap_b32 v217, v219
	global_store_dwordx4 v239, v[216:219], s[10:11] offset:256
	v_add_f32_e32 v64, v2, v3
	s_waitcnt vmcnt(29)
	v_add_u32_e32 v238, 0x120000, v1
	v_add_u32_e32 v239, 0x90000, v240
	v_pk_fma_f32 v[48:49], v[48:49], v[68:69], v[192:193]
	v_pk_fma_f32 v[50:51], v[50:51], v[70:71], v[194:195]
	global_store_dwordx4 v238, v[48:51], s[94:95] offset:0
	v_pk_mul_f32 v[2:3], v[48:49], v[48:49]
	v_pk_fma_f32 v[2:3], v[50:51], v[50:51], v[2:3]
	v_pk_mul_f32 v[192:193], v[48:49], v[92:93]
	v_pk_mul_f32 v[194:195], v[50:51], v[94:95]
	v_cvt_pk_bf16_f32 v220, v192, v193
	v_cvt_pk_bf16_f32 v221, v194, v195
	s_waitcnt vmcnt(28)
	v_pk_fma_f32 v[44:45], v[44:45], v[72:73], v[196:197]
	v_pk_fma_f32 v[46:47], v[46:47], v[74:75], v[198:199]
	global_store_dwordx4 v238, v[44:47], s[94:95] offset:64
	v_pk_fma_f32 v[2:3], v[44:45], v[44:45], v[2:3]
	v_pk_fma_f32 v[2:3], v[46:47], v[46:47], v[2:3]
	v_pk_mul_f32 v[196:197], v[44:45], v[96:97]
	v_pk_mul_f32 v[198:199], v[46:47], v[98:99]
	v_cvt_pk_bf16_f32 v222, v196, v197
	v_cvt_pk_bf16_f32 v223, v198, v199
	s_nop 1
	v_permlane16_swap_b32 v220, v222
	v_permlane16_swap_b32 v221, v223
	global_store_dwordx4 v239, v[220:223], s[10:11] offset:0
	s_waitcnt vmcnt(27)
	v_pk_fma_f32 v[40:41], v[40:41], v[76:77], v[200:201]
	v_pk_fma_f32 v[42:43], v[42:43], v[78:79], v[202:203]
	global_store_dwordx4 v238, v[40:43], s[94:95] offset:512
	v_pk_fma_f32 v[2:3], v[40:41], v[40:41], v[2:3]
	v_pk_fma_f32 v[2:3], v[42:43], v[42:43], v[2:3]
	v_pk_mul_f32 v[200:201], v[40:41], v[100:101]
	v_pk_mul_f32 v[202:203], v[42:43], v[102:103]
	v_cvt_pk_bf16_f32 v224, v200, v201
	v_cvt_pk_bf16_f32 v225, v202, v203
	s_waitcnt vmcnt(26)
	v_pk_fma_f32 v[36:37], v[36:37], v[80:81], v[204:205]
	v_pk_fma_f32 v[38:39], v[38:39], v[82:83], v[206:207]
	global_store_dwordx4 v238, v[36:39], s[94:95] offset:576
	v_pk_fma_f32 v[2:3], v[36:37], v[36:37], v[2:3]
	v_pk_fma_f32 v[2:3], v[38:39], v[38:39], v[2:3]
	v_pk_mul_f32 v[204:205], v[36:37], v[84:85]
	v_pk_mul_f32 v[206:207], v[38:39], v[86:87]
	v_cvt_pk_bf16_f32 v226, v204, v205
	v_cvt_pk_bf16_f32 v227, v206, v207
	s_nop 1
	v_permlane16_swap_b32 v224, v226
	v_permlane16_swap_b32 v225, v227
	global_store_dwordx4 v239, v[224:227], s[10:11] offset:256
	v_add_f32_e32 v48, v2, v3
	s_waitcnt vmcnt(25)
	v_add_u32_e32 v238, 0x140000, v1
	v_add_u32_e32 v239, 0xa0000, v240
	v_pk_fma_f32 v[32:33], v[32:33], v[68:69], v[208:209]
	v_pk_fma_f32 v[34:35], v[34:35], v[70:71], v[210:211]
	global_store_dwordx4 v238, v[32:35], s[94:95] offset:0
	v_pk_mul_f32 v[2:3], v[32:33], v[32:33]
	v_pk_fma_f32 v[2:3], v[34:35], v[34:35], v[2:3]
	v_pk_mul_f32 v[208:209], v[32:33], v[92:93]
	v_pk_mul_f32 v[210:211], v[34:35], v[94:95]
	v_cvt_pk_bf16_f32 v216, v208, v209
	v_cvt_pk_bf16_f32 v217, v210, v211
	s_waitcnt vmcnt(24)
	v_pk_fma_f32 v[28:29], v[28:29], v[72:73], v[212:213]
	v_pk_fma_f32 v[30:31], v[30:31], v[74:75], v[214:215]
	global_store_dwordx4 v238, v[28:31], s[94:95] offset:64
	v_pk_fma_f32 v[2:3], v[28:29], v[28:29], v[2:3]
	v_pk_fma_f32 v[2:3], v[30:31], v[30:31], v[2:3]
	v_pk_mul_f32 v[212:213], v[28:29], v[96:97]
	v_pk_mul_f32 v[214:215], v[30:31], v[98:99]
	v_cvt_pk_bf16_f32 v218, v212, v213
	v_cvt_pk_bf16_f32 v219, v214, v215
	s_nop 1
	v_permlane16_swap_b32 v216, v218
	v_permlane16_swap_b32 v217, v219
	global_store_dwordx4 v239, v[216:219], s[10:11] offset:0
	s_waitcnt vmcnt(23)
	v_pk_fma_f32 v[24:25], v[24:25], v[76:77], v[164:165]
	v_pk_fma_f32 v[26:27], v[26:27], v[78:79], v[166:167]
	global_store_dwordx4 v238, v[24:27], s[94:95] offset:512
	v_pk_fma_f32 v[2:3], v[24:25], v[24:25], v[2:3]
	v_pk_fma_f32 v[2:3], v[26:27], v[26:27], v[2:3]
	v_pk_mul_f32 v[164:165], v[24:25], v[100:101]
	v_pk_mul_f32 v[166:167], v[26:27], v[102:103]
	v_cvt_pk_bf16_f32 v220, v164, v165
	v_cvt_pk_bf16_f32 v221, v166, v167
	s_waitcnt vmcnt(22)
	v_pk_fma_f32 v[20:21], v[20:21], v[80:81], v[168:169]
	v_pk_fma_f32 v[22:23], v[22:23], v[82:83], v[170:171]
	global_store_dwordx4 v238, v[20:23], s[94:95] offset:576
	v_pk_fma_f32 v[2:3], v[20:21], v[20:21], v[2:3]
	v_pk_fma_f32 v[2:3], v[22:23], v[22:23], v[2:3]
	v_pk_mul_f32 v[168:169], v[20:21], v[84:85]
	v_pk_mul_f32 v[170:171], v[22:23], v[86:87]
	v_cvt_pk_bf16_f32 v222, v168, v169
	v_cvt_pk_bf16_f32 v223, v170, v171
	s_nop 1
	v_permlane16_swap_b32 v220, v222
	v_permlane16_swap_b32 v221, v223
	global_store_dwordx4 v239, v[220:223], s[10:11] offset:256
	v_add_f32_e32 v32, v2, v3
	s_waitcnt vmcnt(21)
	v_add_u32_e32 v238, 0x160000, v1
	v_add_u32_e32 v239, 0xb0000, v240
	v_pk_fma_f32 v[16:17], v[16:17], v[68:69], v[172:173]
	v_pk_fma_f32 v[18:19], v[18:19], v[70:71], v[174:175]
	global_store_dwordx4 v238, v[16:19], s[94:95] offset:0
	v_pk_mul_f32 v[2:3], v[16:17], v[16:17]
	v_pk_fma_f32 v[2:3], v[18:19], v[18:19], v[2:3]
	v_pk_mul_f32 v[172:173], v[16:17], v[92:93]
	v_pk_mul_f32 v[174:175], v[18:19], v[94:95]
	v_cvt_pk_bf16_f32 v224, v172, v173
	v_cvt_pk_bf16_f32 v225, v174, v175
	s_waitcnt vmcnt(20)
	v_pk_fma_f32 v[12:13], v[12:13], v[72:73], v[176:177]
	v_pk_fma_f32 v[14:15], v[14:15], v[74:75], v[178:179]
	global_store_dwordx4 v238, v[12:15], s[94:95] offset:64
	v_pk_fma_f32 v[2:3], v[12:13], v[12:13], v[2:3]
	v_pk_fma_f32 v[2:3], v[14:15], v[14:15], v[2:3]
	v_pk_mul_f32 v[176:177], v[12:13], v[96:97]
	v_pk_mul_f32 v[178:179], v[14:15], v[98:99]
	v_cvt_pk_bf16_f32 v226, v176, v177
	v_cvt_pk_bf16_f32 v227, v178, v179
	s_nop 1
	v_permlane16_swap_b32 v224, v226
	v_permlane16_swap_b32 v225, v227
	global_store_dwordx4 v239, v[224:227], s[10:11] offset:0
	s_waitcnt vmcnt(19)
	v_pk_fma_f32 v[8:9], v[8:9], v[76:77], v[180:181]
	v_pk_fma_f32 v[10:11], v[10:11], v[78:79], v[182:183]
	global_store_dwordx4 v238, v[8:11], s[94:95] offset:512
	v_pk_fma_f32 v[2:3], v[8:9], v[8:9], v[2:3]
	v_pk_fma_f32 v[2:3], v[10:11], v[10:11], v[2:3]
	v_pk_mul_f32 v[180:181], v[8:9], v[100:101]
	v_pk_mul_f32 v[182:183], v[10:11], v[102:103]
	v_cvt_pk_bf16_f32 v216, v180, v181
	v_cvt_pk_bf16_f32 v217, v182, v183
	s_waitcnt vmcnt(18)
	v_pk_fma_f32 v[4:5], v[4:5], v[80:81], v[184:185]
	v_pk_fma_f32 v[6:7], v[6:7], v[82:83], v[186:187]
	global_store_dwordx4 v238, v[4:7], s[94:95] offset:576
	v_pk_fma_f32 v[2:3], v[4:5], v[4:5], v[2:3]
	v_pk_fma_f32 v[2:3], v[6:7], v[6:7], v[2:3]
	v_pk_mul_f32 v[184:185], v[4:5], v[84:85]
	v_pk_mul_f32 v[186:187], v[6:7], v[86:87]
	v_cvt_pk_bf16_f32 v218, v184, v185
	v_cvt_pk_bf16_f32 v219, v186, v187
	s_nop 1
	v_permlane16_swap_b32 v216, v218
	v_permlane16_swap_b32 v217, v219
	global_store_dwordx4 v239, v[216:219], s[10:11] offset:256
	v_add_f32_e32 v16, v2, v3
	v_xor_b32_e32 v236, 16, v250
	v_lshlrev_b32_e32 v236, 2, v236
	v_xor_b32_e32 v237, 32, v250
	v_lshlrev_b32_e32 v237, 2, v237
	ds_bpermute_b32 v164, v236, v160
	ds_bpermute_b32 v165, v236, v152
	ds_bpermute_b32 v166, v236, v136
	ds_bpermute_b32 v167, v236, v120
	ds_bpermute_b32 v168, v236, v64
	ds_bpermute_b32 v169, v236, v48
	ds_bpermute_b32 v170, v236, v32
	ds_bpermute_b32 v171, v236, v16
	s_waitcnt lgkmcnt(0)
	v_add_f32_e32 v160, v160, v164
	v_add_f32_e32 v152, v152, v165
	v_add_f32_e32 v136, v136, v166
	v_add_f32_e32 v120, v120, v167
	v_add_f32_e32 v64, v64, v168
	v_add_f32_e32 v48, v48, v169
	v_add_f32_e32 v32, v32, v170
	v_add_f32_e32 v16, v16, v171
	ds_bpermute_b32 v164, v237, v160
	ds_bpermute_b32 v165, v237, v152
	ds_bpermute_b32 v166, v237, v136
	ds_bpermute_b32 v167, v237, v120
	ds_bpermute_b32 v168, v237, v64
	ds_bpermute_b32 v169, v237, v48
	ds_bpermute_b32 v170, v237, v32
	ds_bpermute_b32 v171, v237, v16
	s_waitcnt lgkmcnt(0)
	v_add_f32_e32 v160, v160, v164
	v_add_f32_e32 v152, v152, v165
	v_add_f32_e32 v136, v136, v166
	v_add_f32_e32 v120, v120, v167
	v_add_f32_e32 v64, v64, v168
	v_add_f32_e32 v48, v48, v169
	v_add_f32_e32 v32, v32, v170
	v_add_f32_e32 v16, v16, v171
	s_and_saveexec_b64 s[4:5], s[0:1]
	global_atomic_add_f32 v251, v160, s[12:13] offset:0
	global_atomic_add_f32 v251, v152, s[12:13] offset:64
	global_atomic_add_f32 v251, v136, s[12:13] offset:128
	global_atomic_add_f32 v251, v120, s[12:13] offset:192
	global_atomic_add_f32 v251, v64, s[12:13] offset:512
	global_atomic_add_f32 v251, v48, s[12:13] offset:576
	global_atomic_add_f32 v251, v32, s[12:13] offset:640
	global_atomic_add_f32 v251, v16, s[12:13] offset:704
	s_or_b64 exec, exec, s[4:5]
	s_branch .Lp6_done
.Lp6_quart:
	v_mov_b32_e32 v236, v1
	global_load_dwordx4 v[164:167], v236, s[82:83] offset:0
	global_load_dwordx4 v[168:171], v236, s[82:83] offset:64
	v_add_u32_e32 v237, 0x20000, v1
	global_load_dwordx4 v[172:175], v237, s[82:83] offset:0
	global_load_dwordx4 v[176:179], v237, s[82:83] offset:64
	v_add_u32_e32 v236, 0x40000, v1
	global_load_dwordx4 v[180:183], v236, s[82:83] offset:0
	global_load_dwordx4 v[184:187], v236, s[82:83] offset:64
	v_add_u32_e32 v237, 0x60000, v1
	global_load_dwordx4 v[188:191], v237, s[82:83] offset:0
	global_load_dwordx4 v[192:195], v237, s[82:83] offset:64
	s_waitcnt vmcnt(7)
	v_mov_b32_e32 v238, v1
	v_mov_b32_e32 v239, v240
	v_pk_fma_f32 v[160:161], v[160:161], v[68:69], v[164:165]
	v_pk_fma_f32 v[162:163], v[162:163], v[70:71], v[166:167]
	global_store_dwordx4 v238, v[160:163], s[94:95] offset:0
	v_pk_mul_f32 v[2:3], v[160:161], v[160:161]
	v_pk_fma_f32 v[2:3], v[162:163], v[162:163], v[2:3]
	v_pk_mul_f32 v[164:165], v[160:161], v[92:93]
	v_pk_mul_f32 v[166:167], v[162:163], v[94:95]
	v_cvt_pk_bf16_f32 v216, v164, v165
	v_cvt_pk_bf16_f32 v217, v166, v167
	s_waitcnt vmcnt(7)
	v_pk_fma_f32 v[156:157], v[156:157], v[72:73], v[168:169]
	v_pk_fma_f32 v[158:159], v[158:159], v[74:75], v[170:171]
	global_store_dwordx4 v238, v[156:159], s[94:95] offset:64
	v_pk_fma_f32 v[2:3], v[156:157], v[156:157], v[2:3]
	v_pk_fma_f32 v[2:3], v[158:159], v[158:159], v[2:3]
	v_pk_mul_f32 v[168:169], v[156:157], v[96:97]
	v_pk_mul_f32 v[170:171], v[158:159], v[98:99]
	v_cvt_pk_bf16_f32 v218, v168, v169
	v_cvt_pk_bf16_f32 v219, v170, v171
	s_nop 1
	v_permlane16_swap_b32 v216, v218
	v_permlane16_swap_b32 v217, v219
	global_store_dwordx4 v239, v[216:219], s[10:11] offset:0
	v_add_f32_e32 v160, v2, v3
	s_waitcnt vmcnt(8)
	v_add_u32_e32 v238, 0x20000, v1
	v_add_u32_e32 v239, 0x10000, v240
	v_pk_fma_f32 v[152:153], v[152:153], v[68:69], v[172:173]
	v_pk_fma_f32 v[154:155], v[154:155], v[70:71], v[174:175]
	global_store_dwordx4 v238, v[152:155], s[94:95] offset:0
	v_pk_mul_f32 v[2:3], v[152:153], v[152:153]
	v_pk_fma_f32 v[2:3], v[154:155], v[154:155], v[2:3]
	v_pk_mul_f32 v[172:173], v[152:153], v[92:93]
	v_pk_mul_f32 v[174:175], v[154:155], v[94:95]
	v_cvt_pk_bf16_f32 v220, v172, v173
	v_cvt_pk_bf16_f32 v221, v174, v175
	s_waitcnt vmcnt(8)
	v_pk_fma_f32 v[148:149], v[148:149], v[72:73], v[176:177]
	v_pk_fma_f32 v[150:151], v[150:151], v[74:75], v[178:179]
	global_store_dwordx4 v238, v[148:151], s[94:95] offset:64
	v_pk_fma_f32 v[2:3], v[148:149], v[148:149], v[2:3]
	v_pk_fma_f32 v[2:3], v[150:151], v[150:151], v[2:3]
	v_pk_mul_f32 v[176:177], v[148:149], v[96:97]
	v_pk_mul_f32 v[178:179], v[150:151], v[98:99]
	v_cvt_pk_bf16_f32 v222, v176, v177
	v_cvt_pk_bf16_f32 v223, v178, v179
	s_nop 1
	v_permlane16_swap_b32 v220, v222
	v_permlane16_swap_b32 v221, v223
	global_store_dwordx4 v239, v[220:223], s[10:11] offset:0
	v_add_f32_e32 v152, v2, v3
	s_waitcnt vmcnt(9)
	v_add_u32_e32 v238, 0x40000, v1
	v_add_u32_e32 v239, 0x20000, v240
	v_pk_fma_f32 v[136:137], v[136:137], v[68:69], v[180:181]
	v_pk_fma_f32 v[138:139], v[138:139], v[70:71], v[182:183]
	global_store_dwordx4 v238, v[136:139], s[94:95] offset:0
	v_pk_mul_f32 v[2:3], v[136:137], v[136:137]
	v_pk_fma_f32 v[2:3], v[138:139], v[138:139], v[2:3]
	v_pk_mul_f32 v[180:181], v[136:137], v[92:93]
	v_pk_mul_f32 v[182:183], v[138:139], v[94:95]
	v_cvt_pk_bf16_f32 v224, v180, v181
	v_cvt_pk_bf16_f32 v225, v182, v183
	s_waitcnt vmcnt(9)
	v_pk_fma_f32 v[132:133], v[132:133], v[72:73], v[184:185]
	v_pk_fma_f32 v[134:135], v[134:135], v[74:75], v[186:187]
	global_store_dwordx4 v238, v[132:135], s[94:95] offset:64
	v_pk_fma_f32 v[2:3], v[132:133], v[132:133], v[2:3]
	v_pk_fma_f32 v[2:3], v[134:135], v[134:135], v[2:3]
	v_pk_mul_f32 v[184:185], v[132:133], v[96:97]
	v_pk_mul_f32 v[186:187], v[134:135], v[98:99]
	v_cvt_pk_bf16_f32 v226, v184, v185
	v_cvt_pk_bf16_f32 v227, v186, v187
	s_nop 1
	v_permlane16_swap_b32 v224, v226
	v_permlane16_swap_b32 v225, v227
	global_store_dwordx4 v239, v[224:227], s[10:11] offset:0
	v_add_f32_e32 v136, v2, v3
	s_waitcnt vmcnt(10)
	v_add_u32_e32 v238, 0x60000, v1
	v_add_u32_e32 v239, 0x30000, v240
	v_pk_fma_f32 v[120:121], v[120:121], v[68:69], v[188:189]
	v_pk_fma_f32 v[122:123], v[122:123], v[70:71], v[190:191]
	global_store_dwordx4 v238, v[120:123], s[94:95] offset:0
	v_pk_mul_f32 v[2:3], v[120:121], v[120:121]
	v_pk_fma_f32 v[2:3], v[122:123], v[122:123], v[2:3]
	v_pk_mul_f32 v[188:189], v[120:121], v[92:93]
	v_pk_mul_f32 v[190:191], v[122:123], v[94:95]
	v_cvt_pk_bf16_f32 v216, v188, v189
	v_cvt_pk_bf16_f32 v217, v190, v191
	s_waitcnt vmcnt(10)
	v_pk_fma_f32 v[112:113], v[112:113], v[72:73], v[192:193]
	v_pk_fma_f32 v[114:115], v[114:115], v[74:75], v[194:195]
	global_store_dwordx4 v238, v[112:115], s[94:95] offset:64
	v_pk_fma_f32 v[2:3], v[112:113], v[112:113], v[2:3]
	v_pk_fma_f32 v[2:3], v[114:115], v[114:115], v[2:3]
	v_pk_mul_f32 v[192:193], v[112:113], v[96:97]
	v_pk_mul_f32 v[194:195], v[114:115], v[98:99]
	v_cvt_pk_bf16_f32 v218, v192, v193
	v_cvt_pk_bf16_f32 v219, v194, v195
	s_nop 1
	v_permlane16_swap_b32 v216, v218
	v_permlane16_swap_b32 v217, v219
	global_store_dwordx4 v239, v[216:219], s[10:11] offset:0
	v_add_f32_e32 v120, v2, v3
	v_xor_b32_e32 v236, 16, v250
	v_lshlrev_b32_e32 v236, 2, v236
	v_xor_b32_e32 v237, 32, v250
	v_lshlrev_b32_e32 v237, 2, v237
	ds_bpermute_b32 v164, v236, v160
	ds_bpermute_b32 v165, v236, v152
	ds_bpermute_b32 v166, v236, v136
	ds_bpermute_b32 v167, v236, v120
	s_waitcnt lgkmcnt(0)
	v_add_f32_e32 v160, v160, v164
	v_add_f32_e32 v152, v152, v165
	v_add_f32_e32 v136, v136, v166
	v_add_f32_e32 v120, v120, v167
	ds_bpermute_b32 v164, v237, v160
	ds_bpermute_b32 v165, v237, v152
	ds_bpermute_b32 v166, v237, v136
	ds_bpermute_b32 v167, v237, v120
	s_waitcnt lgkmcnt(0)
	v_add_f32_e32 v160, v160, v164
	v_add_f32_e32 v152, v152, v165
	v_add_f32_e32 v136, v136, v166
	v_add_f32_e32 v120, v120, v167
	s_and_saveexec_b64 s[4:5], s[0:1]
	global_atomic_add_f32 v251, v160, s[12:13] offset:0
	global_atomic_add_f32 v251, v152, s[12:13] offset:64
	global_atomic_add_f32 v251, v136, s[12:13] offset:128
	global_atomic_add_f32 v251, v120, s[12:13] offset:192
	s_or_b64 exec, exec, s[4:5]
